# plus: RWKV LN params issued first in helper prologue, dead zr4 gate preload removed, more seg-1 copy webs skipped, readiness poll reads both stream counters at once
# speedup vs baseline: 1.0801x; 1.0001x over previous
.LBB0_366:
	s_mov_b32 s0, -1
	s_add_i32 s61, s1, 0xffffff50
	v_mbcnt_lo_u32_b32 v0, s0, 0
	v_mbcnt_hi_u32_b32 v0, s0, v0
	v_or_b32_e32 v190, s43, v0
	s_mov_b32 s53, s93
	v_readfirstlane_b32 s0, v190
	s_ashr_i32 s60, s0, 6
	s_lshl_b32 s0, s61, 8
	s_and_b32 s52, s0, 0x7ffff800
	v_writelane_b32 v253, s54, 56
	s_and_b32 s96, s1, 1
	s_and_b32 s97, s60, 3
	s_lshl_b64 s[2:3], s[52:53], 10
	v_writelane_b32 v253, s55, 57
	s_add_u32 s54, s46, s2
	s_addc_u32 s55, s47, s3
	s_lshl_b32 s0, s61, 5
	v_and_b32_e32 v161, 63, v0
	s_and_b32 s2, s0, 0xc0
	v_mov_b32_e32 v0, v161
	s_cmp_lt_i32 s60, 4
	v_writelane_b32 v252, s46, 22
	s_cselect_b64 s[28:29], -1, 0
	s_cmp_gt_i32 s60, 3
	v_and_b32_e32 v1, 15, v0
	v_ashrrev_i32_e32 v0, 2, v0
	v_writelane_b32 v252, s47, 21
	s_mov_b32 s3, s93
	s_cselect_b64 s[30:31], -1, 0
	s_lshl_b32 s0, s97, 4
	v_and_b32_e32 v0, -4, v0
	s_mul_i32 s37, s52, 0x2200
	v_writelane_b32 v252, s2, 27
	v_readlane_b32 s98, v253, 19
	v_readlane_b32 s99, v253, 20
	v_readlane_b32 s100, v252, 17
	v_readlane_b32 s101, v252, 18
	s_lshl_b64 s[98:99], s[98:99], 2
	s_add_u32 s98, s100, s98
	s_addc_u32 s99, s101, s99
	s_lshl_b32 s100, s2, 2
	s_add_u32 s98, s98, s100
	s_addc_u32 s99, s99, 0
	s_or_b32 s100, s2, s84
	v_lshlrev_b32_e32 v192, 2, v161
	global_load_dword v196, v192, s[98:99] offset:1024
	global_load_dword v198, v192, s[98:99]
	global_load_dword v200, v192, s[98:99] offset:2048
	v_add_u32_e32 v192, s100, v161
	v_lshlrev_b32_e32 v192, 2, v192
	global_load_dword v197, v192, s[78:79]
	global_load_dword v201, v192, s[80:81]
	global_load_dword v192, v192, s[76:77]
	v_add_u32_e32 v0, s0, v0
	s_mul_hi_u32 s36, s52, 0x2200
	v_writelane_b32 v252, s3, 28
	v_cmp_eq_u32_e64 s[2:3], v0, v1
	s_add_u32 s38, s44, s37
	v_or_b32_e32 v2, 1, v0
	v_writelane_b32 v252, s2, 1
	s_addc_u32 s39, s45, s36
	s_lshl_b64 s[36:37], s[52:53], 9
	v_writelane_b32 v252, s3, 2
	v_cmp_eq_u32_e64 s[2:3], v2, v1
	s_add_u32 s36, s72, s36
	v_or_b32_e32 v4, 2, v0
	v_writelane_b32 v252, s2, 3
	v_or_b32_e32 v5, 3, v0
	v_or_b32_e32 v6, 16, v1
	s_addc_u32 s37, s73, s37
	v_writelane_b32 v252, s3, 4
	v_cmp_eq_u32_e64 s[6:7], v4, v1
	v_cmp_eq_u32_e64 s[8:9], v5, v1
	v_cmp_eq_u32_e64 s[10:11], v0, v6
	v_cmp_eq_u32_e64 s[12:13], v2, v6
	v_cmp_eq_u32_e64 s[14:15], v4, v6
	v_cmp_eq_u32_e64 s[16:17], v5, v6
	v_or_b32_e32 v6, 32, v1
	v_or_b32_e32 v1, 48, v1
	s_add_u32 s56, s36, 0xde00000
	v_cmp_eq_u32_e64 s[18:19], v0, v6
	v_cmp_eq_u32_e64 s[20:21], v2, v6
	v_cmp_eq_u32_e64 s[22:23], v4, v6
	v_cmp_eq_u32_e64 s[24:25], v5, v6
	v_cmp_eq_u32_e64 s[26:27], v0, v1
	v_cmp_eq_u32_e64 s[2:3], v2, v1
	v_cmp_eq_u32_e64 s[4:5], v4, v1
	v_cmp_eq_u32_e64 s[34:35], v5, v1
	v_writelane_b32 v252, s38, 29
	s_addc_u32 s57, s37, 0
	s_and_b64 vcc, exec, s[28:29]
	v_writelane_b32 v253, s43, 58
	v_writelane_b32 v252, s39, 30
	s_cbranch_vccnz .LBB0_420
	v_mov_b32_e32 v0, v190
	s_lshl_b32 s46, s96, 10
	v_add_u32_e32 v32, 0xffffff00, v0
	s_movk_i32 s98, 0x140
	v_cmp_gt_i32_e32 vcc, s98, v0
	s_and_saveexec_b64 s[98:99], vcc
	s_cbranch_execz .Lrw_ln_skip
	v_readlane_b32 s100, v252, 27
	s_or_b32 s100, s100, s84
	v_add_u32_e32 v254, s100, v0
	v_lshlrev_b32_e32 v254, 2, v254
	v_readlane_b32 s100, v253, 39
	v_readlane_b32 s101, v253, 40
	global_load_dword v255, v254, s[82:83] offset:-1024
	s_nop 3
	global_load_dword v251, v254, s[100:101] offset:-1024
.Lrw_ln_skip:
	s_or_b64 exec, exec, s[98:99]
	s_add_i32 s58, s46, -1
	v_ashrrev_i32_e32 v2, 4, v32
	v_lshlrev_b32_e32 v1, 2, v0
	v_add_u32_e32 v2, s58, v2
	s_movk_i32 s36, 0x510
	v_and_b32_e32 v1, 60, v1
	v_cmp_gt_i32_e32 vcc, s36, v0
	v_cmp_lt_i32_e64 s[36:37], -1, v2
	s_and_b64 s[38:39], vcc, s[36:37]
	v_mov_b32_e32 v4, 0
	v_lshlrev_b32_e32 v24, 2, v1
	v_mov_b32_e32 v8, 0
	v_mov_b32_e32 v9, 0
	v_mov_b32_e32 v10, 0
	v_mov_b32_e32 v11, 0
	s_and_saveexec_b64 s[36:37], s[38:39]
	s_cbranch_execz .LBB0_369
	v_lshlrev_b64 v[6:7], 10, v[2:3]
	v_readlane_b32 s38, v252, 27
	v_lshl_add_u64 v[6:7], s[54:55], 0, v[6:7]
	s_lshl_b32 s92, s38, 2
	v_lshl_add_u64 v[6:7], v[6:7], 0, s[92:93]
	v_mov_b32_e32 v25, v3
	v_lshl_add_u64 v[6:7], v[6:7], 0, v[24:25]
	global_load_dwordx4 v[8:11], v[6:7], off
	v_readlane_b32 s39, v252, 28

.LBB0_417:
	s_or_b64 exec, exec, s[36:37]
	s_movk_i32 s36, 0x140
	v_cmp_gt_i32_e32 vcc, s36, v0
	s_and_saveexec_b64 s[36:37], vcc
	s_cbranch_execz .LBB0_419
	v_readlane_b32 s38, v252, 27
	s_or_b32 s92, s38, s84
	v_ashrrev_i32_e32 v1, 31, v0
	v_lshl_add_u64 v[0:1], s[92:93], 0, v[0:1]
	v_lshlrev_b64 v[0:1], 2, v[0:1]
	v_readlane_b32 s40, v253, 39
	s_waitcnt vmcnt(0)
	v_lshl_add_u64 v[4:5], s[82:83], 0, v[0:1]
	v_readlane_b32 s41, v253, 40
	v_mov_b32_e32 v2, v255
	v_readlane_b32 s39, v252, 28
	v_lshl_add_u64 v[0:1], s[40:41], 0, v[0:1]
	v_mov_b32_e32 v0, v251
	v_lshl_add_u32 v1, v32, 2, 0
	v_add_u32_e32 v4, 0x27600, v1
	v_readlane_b32 s42, v253, 41
	v_readlane_b32 s43, v253, 42
	v_add_u32_e32 v1, 0x27700, v1
	s_waitcnt vmcnt(1)
	ds_write_b32 v4, v2
	s_waitcnt vmcnt(0)
	ds_write_b32 v1, v0

.LBB0_455:
	s_cmp_lg_u64 s[40:41], 0
	s_cbranch_scc1 .Lrw_455_full
	s_andn2_b64 vcc, exec, s[28:29]
	s_branch .Lrw_455_done

.Lrw_455_done:
	s_cbranch_vccnz .LBB0_485
	v_mov_b32_e32 v1, v161
	v_readlane_b32 s12, v252, 44
	v_and_b32_e32 v59, 15, v1
	v_and_b32_e32 v9, -16, v1
	s_waitcnt vmcnt(0)
	s_cmp_lg_u64 s[40:41], 0
	s_cbranch_scc1 .Lrz_skip2
	s_lshl_b32 s98, s0, 8
	s_add_i32 s98, s98, 0x20a00
	v_lshl_add_u32 v36, v161, 4, s98
	v_lshlrev_b32_e32 v32, 16, v184
	v_and_b32_e32 v33, 0xffff0000, v184
	v_mul_f32_e32 v34, 0xbfb8aa3b, v32
	v_mul_f32_e32 v35, 0xbfb8aa3b, v33
	v_exp_f32_e32 v34, v34
	v_exp_f32_e32 v35, v35
	s_nop 0
	v_add_f32_e32 v34, 1.0, v34
	v_add_f32_e32 v35, 1.0, v35
	v_rcp_f32_e32 v34, v34
	v_rcp_f32_e32 v35, v35
	s_nop 0
	v_pk_mul_f32 v[76:77], v[34:35], v[32:33]
	v_lshlrev_b32_e32 v32, 16, v185
	v_and_b32_e32 v33, 0xffff0000, v185
	v_mul_f32_e32 v34, 0xbfb8aa3b, v32
	v_mul_f32_e32 v35, 0xbfb8aa3b, v33
	v_exp_f32_e32 v34, v34
	v_exp_f32_e32 v35, v35
	s_nop 0
	v_add_f32_e32 v34, 1.0, v34
	v_add_f32_e32 v35, 1.0, v35
	v_rcp_f32_e32 v34, v34
	v_rcp_f32_e32 v35, v35
	s_nop 0
	v_pk_mul_f32 v[78:79], v[34:35], v[32:33]
	ds_write_b128 v36, v[76:79]
	v_lshlrev_b32_e32 v32, 16, v186
	v_and_b32_e32 v33, 0xffff0000, v186
	v_mul_f32_e32 v34, 0xbfb8aa3b, v32
	v_mul_f32_e32 v35, 0xbfb8aa3b, v33
	v_exp_f32_e32 v34, v34
	v_exp_f32_e32 v35, v35
	s_nop 0
	v_add_f32_e32 v34, 1.0, v34
	v_add_f32_e32 v35, 1.0, v35
	v_rcp_f32_e32 v34, v34
	v_rcp_f32_e32 v35, v35
	s_nop 0
	v_pk_mul_f32 v[86:87], v[34:35], v[32:33]
	v_lshlrev_b32_e32 v32, 16, v187
	v_and_b32_e32 v33, 0xffff0000, v187
	v_mul_f32_e32 v34, 0xbfb8aa3b, v32
	v_mul_f32_e32 v35, 0xbfb8aa3b, v33
	v_exp_f32_e32 v34, v34
	v_exp_f32_e32 v35, v35
	s_nop 0
	v_add_f32_e32 v34, 1.0, v34
	v_add_f32_e32 v35, 1.0, v35
	v_rcp_f32_e32 v34, v34
	v_rcp_f32_e32 v35, v35
	s_nop 0
	v_pk_mul_f32 v[88:89], v[34:35], v[32:33]
	ds_write_b128 v36, v[86:89] offset:1024
	v_lshlrev_b32_e32 v32, 16, v188
	v_and_b32_e32 v33, 0xffff0000, v188
	v_mul_f32_e32 v34, 0xbfb8aa3b, v32
	v_mul_f32_e32 v35, 0xbfb8aa3b, v33
	v_exp_f32_e32 v34, v34
	v_exp_f32_e32 v35, v35
	s_nop 0
	v_add_f32_e32 v34, 1.0, v34
	v_add_f32_e32 v35, 1.0, v35
	v_rcp_f32_e32 v34, v34
	v_rcp_f32_e32 v35, v35
	s_nop 0
	v_pk_mul_f32 v[76:77], v[34:35], v[32:33]
	v_lshlrev_b32_e32 v32, 16, v189
	v_and_b32_e32 v33, 0xffff0000, v189
	v_mul_f32_e32 v34, 0xbfb8aa3b, v32
	v_mul_f32_e32 v35, 0xbfb8aa3b, v33
	v_exp_f32_e32 v34, v34
	v_exp_f32_e32 v35, v35
	s_nop 0
	v_add_f32_e32 v34, 1.0, v34
	v_add_f32_e32 v35, 1.0, v35
	v_rcp_f32_e32 v34, v34
	v_rcp_f32_e32 v35, v35
	s_nop 0
	v_pk_mul_f32 v[78:79], v[34:35], v[32:33]
	ds_write_b128 v36, v[76:79] offset:2048
	v_lshlrev_b32_e32 v32, 16, v224
	v_and_b32_e32 v33, 0xffff0000, v224
	v_mul_f32_e32 v34, 0xbfb8aa3b, v32
	v_mul_f32_e32 v35, 0xbfb8aa3b, v33
	v_exp_f32_e32 v34, v34
	v_exp_f32_e32 v35, v35
	s_nop 0
	v_add_f32_e32 v34, 1.0, v34
	v_add_f32_e32 v35, 1.0, v35
	v_rcp_f32_e32 v34, v34
	v_rcp_f32_e32 v35, v35
	s_nop 0
	v_pk_mul_f32 v[86:87], v[34:35], v[32:33]
	v_lshlrev_b32_e32 v32, 16, v225
	v_and_b32_e32 v33, 0xffff0000, v225
	v_mul_f32_e32 v34, 0xbfb8aa3b, v32
	v_mul_f32_e32 v35, 0xbfb8aa3b, v33
	v_exp_f32_e32 v34, v34
	v_exp_f32_e32 v35, v35
	s_nop 0
	v_add_f32_e32 v34, 1.0, v34
	v_add_f32_e32 v35, 1.0, v35
	v_rcp_f32_e32 v34, v34
	v_rcp_f32_e32 v35, v35
	s_nop 0
	v_pk_mul_f32 v[88:89], v[34:35], v[32:33]
	ds_write_b128 v36, v[86:89] offset:3072

.LBB0_485:
	s_and_b64 vcc, exec, s[10:11]
	s_mov_b64 s[8:9], -1
	s_waitcnt lgkmcnt(0)
	s_barrier
	s_cbranch_vccnz .LBB0_497
	v_readlane_b32 s8, v252, 1
	s_waitcnt vmcnt(1)
	v_mov_b32_e32 v4, v161
	v_readlane_b32 s9, v252, 2
	s_andn2_b64 vcc, exec, s[8:9]
	s_waitcnt vmcnt(0)
	v_and_b32_e32 v2, 15, v4
.LBB0_488:
	v_and_b32_e32 v8, -16, v4
	v_add_u32_e32 v59, 0, v8
	v_mad_u32_u24 v9, v2, s89, v59
	ds_read_b128 v[4:7], v9 offset:64512
	v_or_b32_e32 v10, s0, v2
	v_mad_u32_u24 v10, v10, s89, v59
	ds_read_b128 v[144:147], v10 offset:9216
	ds_read_b128 v[28:31], v9 offset:64576
	ds_read_b128 v[140:143], v10 offset:9280
	s_add_i32 s8, 0, 0x20a00
	v_mul_u32_u24_e32 v128, 0x90, v2
	v_cndmask_b32_e64 v2, 0, 1, s[40:41]
	v_add_u32_e32 v8, s8, v8
	s_waitcnt lgkmcnt(2)
	v_mfma_f32_16x16x32_bf16 v[4:7], v[4:7], v[144:147], 0
	v_mov_b64_e32 v[106:107], v[74:75]
	v_cmp_ne_u32_e64 s[8:9], 1, v2
	s_andn2_b64 vcc, exec, s[40:41]
	s_waitcnt lgkmcnt(0)
	v_mfma_f32_16x16x32_bf16 v[124:127], v[28:31], v[140:143], v[4:7]
	v_add_u32_e32 v2, v8, v128
	v_mov_b64_e32 v[104:105], v[72:73]
	v_mov_b64_e32 v[102:103], v[70:71]
	v_mov_b64_e32 v[100:101], v[68:69]
	v_mov_b64_e32 v[98:99], v[66:67]
	v_mov_b64_e32 v[96:97], v[64:65]
	v_mov_b64_e32 v[94:95], v[62:63]
	v_mov_b64_e32 v[92:93], v[60:61]
	v_mov_b32_e32 v4, v52
	v_mov_b32_e32 v5, v53
	v_mov_b32_e32 v6, v54
	v_mov_b32_e32 v7, v55
	s_cbranch_vccnz .LBB0_490
	ds_read_b128 v[4:7], v2
	ds_read_b128 v[20:23], v2 offset:64
	v_mov_b32_e32 v8, v56
	v_mov_b32_e32 v9, v57
	v_mov_b32_e32 v10, v58
	s_waitcnt lgkmcnt(1)
	v_mfma_f32_16x16x32_bf16 v[4:7], v[4:7], v[144:147], 0
	s_waitcnt lgkmcnt(0)
	v_mfma_f32_16x16x32_bf16 v[4:7], v[20:23], v[140:143], v[4:7]
	v_mov_b64_e32 v[106:107], v[18:19]
	v_mov_b64_e32 v[50:51], v[18:19]
	v_mov_b64_e32 v[34:35], v[18:19]
	v_mov_b64_e32 v[90:91], v[18:19]
	v_mov_b64_e32 v[104:105], v[16:17]
	v_mov_b64_e32 v[102:103], v[14:15]
	v_mov_b64_e32 v[100:101], v[12:13]
	v_mov_b64_e32 v[98:99], v[10:11]
	v_mov_b64_e32 v[96:97], v[8:9]
	v_mov_b64_e32 v[94:95], v[6:7]
	v_mov_b64_e32 v[92:93], v[4:5]
	v_mov_b64_e32 v[46:47], v[14:15]
	v_mov_b64_e32 v[44:45], v[12:13]
	v_mov_b64_e32 v[42:43], v[10:11]
	v_mov_b64_e32 v[40:41], v[8:9]
	v_mov_b64_e32 v[38:39], v[6:7]
	v_mov_b64_e32 v[36:37], v[4:5]
	v_mov_b64_e32 v[32:33], v[16:17]
	v_mov_b64_e32 v[26:27], v[10:11]
	v_mov_b64_e32 v[24:25], v[8:9]
	v_mov_b64_e32 v[22:23], v[6:7]
	v_mov_b64_e32 v[20:21], v[4:5]
	v_mov_b64_e32 v[88:89], v[16:17]
	v_mov_b64_e32 v[86:87], v[14:15]
	v_mov_b64_e32 v[84:85], v[12:13]
	v_mov_b64_e32 v[78:79], v[6:7]
	v_mov_b64_e32 v[76:77], v[4:5]
	v_mov_b64_e32 v[48:49], v[16:17]
	v_mov_b64_e32 v[30:31], v[14:15]
	v_mov_b64_e32 v[28:29], v[12:13]
	v_mov_b64_e32 v[82:83], v[10:11]
	v_mov_b64_e32 v[80:81], v[8:9]

.LBB0_548:
	v_readlane_b32 s14, v252, 1
	v_readlane_b32 s15, v252, 2
	v_lshlrev_b32_e32 v40, 2, v2
	s_mov_b64 s[12:13], -1
	s_and_b64 vcc, exec, s[14:15]
	s_cbranch_vccz .LBB0_550
	v_add_f32_e32 v2, v20, v21
	v_add_f32_e32 v8, v22, v23
	v_add_f32_e32 v2, v2, v8
	v_add_f32_e32 v8, v24, v25
	v_add_f32_e32 v9, v26, v27
	v_add_f32_e32 v2, 0, v2
	v_add_f32_e32 v8, v8, v9
	v_add_f32_e32 v2, v2, v8
	v_add_f32_e32 v8, v32, v33
	v_add_f32_e32 v9, v34, v35
	v_add_f32_e32 v8, v8, v9
	v_add_f32_e32 v2, v2, v8
	v_mov_b32_e32 v8, v37
	v_mov_b32_e32 v9, v38
	v_mov_b32_e32 v10, v36
	v_mov_b32_e32 v11, v39
	v_pk_add_f32 v[8:9], v[8:9], v[10:11]
	s_add_i32 s12, s0, s42
	v_add_f32_e32 v8, v8, v9
	v_and_b32_e32 v9, 64, v234
	v_add_f32_e32 v2, v2, v8
	v_xor_b32_e32 v8, 16, v234
	v_add_u32_e32 v9, 64, v9
	v_cmp_lt_i32_e32 vcc, v8, v9
	v_lshlrev_b32_e32 v56, 16, v188
	v_and_b32_e32 v57, 0xffff0000, v188
	v_cndmask_b32_e32 v8, v234, v8, vcc
	v_lshlrev_b32_e32 v16, 2, v8
	ds_bpermute_b32 v8, v16, v2
	v_readlane_b32 s14, v252, 27
	v_readlane_b32 s15, v252, 28
	s_waitcnt lgkmcnt(0)
	v_add_f32_e32 v2, v2, v8
	v_xor_b32_e32 v8, 32, v234
	v_cmp_lt_i32_e32 vcc, v8, v9
	v_add_u32_e32 v44, s14, v40
	v_ashrrev_i32_e32 v45, 31, v44
	v_cndmask_b32_e32 v8, v234, v8, vcc
	v_lshlrev_b32_e32 v17, 2, v8
	ds_bpermute_b32 v8, v17, v2
	s_waitcnt lgkmcnt(0)
	v_add_f32_e32 v18, v2, v8
	v_fmamk_f32 v149, v18, 0xbc800000, v21
	v_fmamk_f32 v148, v18, 0xbc800000, v20
	v_fmamk_f32 v155, v18, 0xbc800000, v23
	v_fmamk_f32 v154, v18, 0xbc800000, v22
	v_pk_mul_f32 v[8:9], v[154:155], v[154:155]
	v_pk_mul_f32 v[10:11], v[148:149], v[148:149]
	v_fmamk_f32 v153, v18, 0xbc800000, v25
	v_pk_mov_b32 v[12:13], v[10:11], v[8:9] op_sel:[1,0]
	v_mov_b32_e32 v11, v9
	v_fmamk_f32 v152, v18, 0xbc800000, v24
	v_fmamk_f32 v151, v18, 0xbc800000, v27
	v_fmamk_f32 v150, v18, 0xbc800000, v26
	v_pk_add_f32 v[8:9], v[12:13], v[10:11]
	v_pk_mul_f32 v[10:11], v[150:151], v[150:151]
	v_pk_mul_f32 v[12:13], v[152:153], v[152:153]
	v_fmamk_f32 v172, v18, 0xbc800000, v32
	v_pk_mov_b32 v[14:15], v[12:13], v[10:11] op_sel:[1,0]
	v_mov_b32_e32 v13, v11
	v_fmamk_f32 v168, v18, 0xbc800000, v34
	v_fmamk_f32 v173, v18, 0xbc800000, v33
	v_mul_f32_e32 v2, v172, v172
	v_pk_add_f32 v[10:11], v[14:15], v[12:13]
	v_fmamk_f32 v169, v18, 0xbc800000, v35
	v_pk_fma_f32 v[12:13], v[172:173], v[172:173], v[2:3] op_sel_hi:[1,1,0]
	v_mul_f32_e32 v2, v168, v168
	v_pk_add_f32 v[8:9], v[8:9], v[8:9] op_sel_hi:[0,1]
	v_pk_add_f32 v[10:11], v[10:11], v[10:11] op_sel_hi:[0,1]
	v_pk_fma_f32 v[14:15], v[168:169], v[168:169], v[2:3] op_sel_hi:[1,1,0]
	v_fmamk_f32 v171, v18, 0xbc800000, v39
	v_fmamk_f32 v170, v18, 0xbc800000, v38
	v_fmamk_f32 v175, v18, 0xbc800000, v37
	v_fmamk_f32 v174, v18, 0xbc800000, v36
	v_mul_f32_e32 v12, v174, v174
	v_mul_f32_e32 v14, v175, v175
	v_mul_f32_e32 v8, v170, v170
	v_mul_f32_e32 v10, v171, v171
	v_pk_add_f32 v[12:13], v[12:13], v[14:15]
	v_pk_add_f32 v[8:9], v[8:9], v[10:11]
	s_nop 0
	v_pk_add_f32 v[8:9], v[12:13], v[8:9]
	s_nop 0
	v_add_f32_e32 v2, v8, v9
	ds_bpermute_b32 v8, v16, v2
	s_waitcnt lgkmcnt(0)
	v_add_f32_e32 v2, v2, v8
	ds_bpermute_b32 v8, v17, v2
	v_lshrrev_b32_e32 v17, 2, v59
	v_or_b32_e32 v41, v40, v17
	s_waitcnt lgkmcnt(0)
	v_add_f32_e32 v2, v2, v8
	v_fmamk_f32 v2, v2, 0x3c800000, v156
	v_cmp_gt_f32_e32 vcc, s75, v2
	v_mul_f32_e32 v8, 0x4b800000, v2
	s_nop 0
	v_cndmask_b32_e32 v2, v2, v8, vcc
	v_rsq_f32_e32 v2, v2
	s_nop 0
	v_mul_f32_e32 v8, 0x45800000, v2
	v_cndmask_b32_e32 v16, v2, v8, vcc
	v_add_u32_e32 v84, s12, v59
	v_readlane_b32 s12, v252, 38
	v_subrev_u32_e32 v84, 63, v84
	v_lshlrev_b32_e32 v8, 3, v46
	v_and_b32_e32 v8, 24, v8
	v_add_u32_e32 v8, s55, v8
	v_mad_u32_u24 v61, v41, s89, v8
	v_lshl_add_u32 v9, v59, 2, s12
	ds_read_b32 v18, v9
	v_lshlrev_b32_e32 v10, 2, v40
	v_add_u32_e32 v19, 0x27600, v10
	v_add_u32_e32 v58, 0x27700, v10
	s_lshl_b32 s13, s0, 8
	s_add_i32 s13, s13, 0x20a00
	v_lshl_add_u32 v74, v46, 4, s13
	v_lshlrev_b32_e32 v56, 11, v84
	v_lshl_add_u32 v56, v44, 1, v56
	ds_read_b128 v[62:65], v19
	ds_read_b128 v[66:69], v58
	ds_read_b64_tr_b16 v[188:189], v61 offset:55296
	ds_read_b128 v[70:73], v74
	ds_read_b128 v[76:79], v19 offset:64
	ds_read_b128 v[184:187], v58 offset:64
	ds_read_b64_tr_b16 v[250:251], v61 offset:57600
	ds_read_b128 v[52:55], v74 offset:1024
	v_readlane_b32 s12, v252, 36
	v_readlane_b32 s13, v252, 37
	s_waitcnt lgkmcnt(4)
	v_pk_mul_f32 v[8:9], v[148:149], v[16:17] op_sel_hi:[1,0]
	v_pk_mul_f32 v[10:11], v[154:155], v[16:17] op_sel_hi:[1,0]
	v_pk_fma_f32 v[8:9], v[62:63], v[8:9], v[66:67]
	v_pk_fma_f32 v[10:11], v[64:65], v[10:11], v[68:69]
	v_lshlrev_b32_e32 v12, 16, v188
	v_and_b32_e32 v13, 0xffff0000, v188
	v_lshlrev_b32_e32 v14, 16, v189
	v_and_b32_e32 v15, 0xffff0000, v189
	v_pk_fma_f32 v[8:9], v[18:19], v[12:13], v[8:9] op_sel_hi:[0,1,1]
	v_pk_fma_f32 v[10:11], v[18:19], v[14:15], v[10:11] op_sel_hi:[0,1,1]
	v_pk_mul_f32 v[8:9], v[70:71], v[8:9]
	v_pk_mul_f32 v[10:11], v[72:73], v[10:11]
	v_cvt_pk_bf16_f32 v8, v8, v9
	v_cvt_pk_bf16_f32 v9, v10, v11
	global_store_dwordx2 v56, v[8:9], s[12:13] offset:1536
	ds_read_b128 v[62:65], v19 offset:128
	ds_read_b128 v[66:69], v58 offset:128
	ds_read_b64_tr_b16 v[188:189], v61 offset:59904
	ds_read_b128 v[70:73], v74 offset:2048
	s_waitcnt lgkmcnt(4)
	v_pk_mul_f32 v[8:9], v[152:153], v[16:17] op_sel_hi:[1,0]
	v_pk_mul_f32 v[10:11], v[150:151], v[16:17] op_sel_hi:[1,0]
	v_pk_fma_f32 v[8:9], v[76:77], v[8:9], v[184:185]
	v_pk_fma_f32 v[10:11], v[78:79], v[10:11], v[186:187]
	v_lshlrev_b32_e32 v12, 16, v250
	v_and_b32_e32 v13, 0xffff0000, v250
	v_lshlrev_b32_e32 v14, 16, v251
	v_and_b32_e32 v15, 0xffff0000, v251
	v_pk_fma_f32 v[8:9], v[18:19], v[12:13], v[8:9] op_sel_hi:[0,1,1]
	v_pk_fma_f32 v[10:11], v[18:19], v[14:15], v[10:11] op_sel_hi:[0,1,1]
	v_pk_mul_f32 v[8:9], v[52:53], v[8:9]
	v_pk_mul_f32 v[10:11], v[54:55], v[10:11]
	v_cvt_pk_bf16_f32 v8, v8, v9
	v_cvt_pk_bf16_f32 v9, v10, v11
	global_store_dwordx2 v56, v[8:9], s[12:13] offset:1568
	ds_read_b128 v[76:79], v19 offset:192
	ds_read_b128 v[184:187], v58 offset:192
	ds_read_b64_tr_b16 v[250:251], v61 offset:62208
	ds_read_b128 v[52:55], v74 offset:3072
	s_waitcnt lgkmcnt(4)
	v_pk_mul_f32 v[8:9], v[172:173], v[16:17] op_sel_hi:[1,0]
	v_pk_mul_f32 v[10:11], v[168:169], v[16:17] op_sel_hi:[1,0]
	v_pk_fma_f32 v[8:9], v[62:63], v[8:9], v[66:67]
	v_pk_fma_f32 v[10:11], v[64:65], v[10:11], v[68:69]
	v_lshlrev_b32_e32 v12, 16, v188
	v_and_b32_e32 v13, 0xffff0000, v188
	v_lshlrev_b32_e32 v14, 16, v189
	v_and_b32_e32 v15, 0xffff0000, v189
	v_pk_fma_f32 v[8:9], v[18:19], v[12:13], v[8:9] op_sel_hi:[0,1,1]
	v_pk_fma_f32 v[10:11], v[18:19], v[14:15], v[10:11] op_sel_hi:[0,1,1]
	v_pk_mul_f32 v[8:9], v[70:71], v[8:9]
	v_pk_mul_f32 v[10:11], v[72:73], v[10:11]
	v_cvt_pk_bf16_f32 v8, v8, v9
	v_cvt_pk_bf16_f32 v9, v10, v11
	global_store_dwordx2 v56, v[8:9], s[12:13] offset:1600
	s_waitcnt lgkmcnt(0)
	v_pk_mul_f32 v[8:9], v[174:175], v[16:17] op_sel_hi:[1,0]
	v_pk_mul_f32 v[10:11], v[170:171], v[16:17] op_sel_hi:[1,0]
	v_pk_fma_f32 v[8:9], v[76:77], v[8:9], v[184:185]
	v_pk_fma_f32 v[10:11], v[78:79], v[10:11], v[186:187]
	v_lshlrev_b32_e32 v12, 16, v250
	v_and_b32_e32 v13, 0xffff0000, v250
	v_lshlrev_b32_e32 v14, 16, v251
	v_and_b32_e32 v15, 0xffff0000, v251
	v_pk_fma_f32 v[8:9], v[18:19], v[12:13], v[8:9] op_sel_hi:[0,1,1]
	v_pk_fma_f32 v[10:11], v[18:19], v[14:15], v[10:11] op_sel_hi:[0,1,1]
	v_pk_mul_f32 v[8:9], v[52:53], v[8:9]
	v_pk_mul_f32 v[10:11], v[54:55], v[10:11]
	v_cvt_pk_bf16_f32 v8, v8, v9
	v_cvt_pk_bf16_f32 v9, v10, v11
	global_store_dwordx2 v56, v[8:9], s[12:13] offset:1632
	s_mov_b64 s[12:13], 0
	s_branch .LBB0_562

.Lrw_wd:
	s_cmp_ge_u32 s66, s59
	s_barrier
	s_cbranch_scc1 .LBB0_572
	s_branch .LBB0_422

.LBB0_970:
	global_load_dword v2, v3, s[26:27] sc1
	global_load_dword v18, v3, s[28:29] sc1
	s_waitcnt vmcnt(0)
	v_cmp_gt_u32_e64 s[34:35], s23, v2
	v_cmp_gt_u32_e64 s[98:99], s23, v18
	s_or_b64 s[34:35], s[34:35], s[98:99]
	s_and_b64 vcc, exec, s[34:35]
	s_cbranch_vccnz .LBB0_974
	s_mov_b64 s[34:35], 0
	s_and_b64 vcc, exec, s[30:31]
	s_cbranch_vccz .LBB0_974
	global_load_dword v2, v3, s[14:15] offset:64 sc1
	s_waitcnt vmcnt(0)
	v_cmp_gt_u32_e64 s[34:35], 16, v2
